# GEMM K-loops: end-of-tile vmcnt(0)+barrier placed after the last fragment-read wait (MFMA 29 of the second half)
# speedup vs baseline: 1.0739x; 1.0004x over previous
; #define G3_LDA(buf, kt, i) __builtin_amdgcn_global_load_lds((const unsigned*)(ga + (size_t)((i) * 64) * lda + (kt) * 64), (lds_u32*)(sdst + (buf) * STAGE + (i) * 8192), 16, 0, 0)
; #define G3_LDB(buf, kt, i) __builtin_amdgcn_global_load_lds((const unsigned*)(gb + (size_t)((i) * 64) * ldb + (kt) * 64), (lds_u32*)(sdst + (buf) * STAGE + B_OFF + (i) * 8192), 16, 0, 0)
; DI void gemm3_mainloop(const int wave8, const int lane, const bf16_t* __restrict__ A, int lda, const bf16_t* __restrict__ Bt, int ldb, int K,
;                        unsigned char* smem, f32x4 (&acc)[8][4]) {
;     ...
;     asm volatile("s_waitcnt vmcnt(0)" ::: "memory");
;     G3_LDA(0, 0, 0); G3_LDA(0, 0, 1); G3_LDA(0, 0, 2); G3_LDA(0, 0, 3); G3_LDB(0, 0, 0); G3_LDB(0, 0, 1); G3_LDB(0, 0, 2); G3_LDB(0, 0, 3);
;     asm volatile("s_waitcnt vmcnt(0)" ::: "memory");
;     __builtin_amdgcn_s_barrier();
;     for (int kt = 0; kt < nk; kt += 2) { G3_STEP(0, 1, kt); G3_STEP(1, 0, kt + 1); }
.LBB0_90:
	ds_read_b128 v[128:131], v148 offset:32768
	ds_read_b128 v[168:171], v149
	ds_read_b128 v[156:159], v148 offset:34816
	ds_read_b128 v[160:163], v148 offset:36864
	ds_read_b128 v[164:167], v148 offset:38912
	ds_read_b128 v[172:175], v149 offset:2048
	ds_read_b128 v[176:179], v149 offset:4096
	ds_read_b128 v[180:183], v149 offset:6144
	ds_read_b128 v[184:187], v149 offset:8192
	ds_read_b128 v[188:191], v149 offset:10240
	ds_read_b128 v[192:195], v149 offset:12288
	ds_read_b128 v[196:199], v149 offset:14336
	s_waitcnt lgkmcnt(10)
	v_mfma_f32_16x16x32_bf16 v[112:115], v[128:131], v[168:171], v[112:115]
	s_mov_b64 s[8:9], 0x19dc5080
	s_mov_b32 m0, s88
	s_add_i32 s18, s6, 1
	s_waitcnt lgkmcnt(9)
	v_mfma_f32_16x16x32_bf16 v[124:127], v[156:159], v[168:171], v[124:127]
	s_add_i32 s7, s6, 2
	s_cmp_lt_u32 s6, 30
	s_waitcnt lgkmcnt(8)
	v_mfma_f32_16x16x32_bf16 v[120:123], v[160:163], v[168:171], v[120:123]
	s_waitcnt lgkmcnt(7)
	v_mfma_f32_16x16x32_bf16 v[116:119], v[164:167], v[168:171], v[116:119]
	v_lshl_add_u64 v[168:169], v[138:139], 0, v[132:133]
	v_lshl_add_u64 v[170:171], v[168:169], 0, s[8:9]
	s_mov_b64 s[8:9], 0x19e07080
	global_load_lds_dwordx4 v[170:171], off
	v_lshl_add_u64 v[170:171], v[168:169], 0, s[8:9]
	s_mov_b32 m0, s92
	s_mov_b64 s[8:9], 0x19e49080
	s_waitcnt lgkmcnt(6)
	v_mfma_f32_16x16x32_bf16 v[96:99], v[128:131], v[172:175], v[96:99]
	v_lshl_add_u64 v[138:139], v[138:139], 0, s[34:35]
	v_mfma_f32_16x16x32_bf16 v[108:111], v[156:159], v[172:175], v[108:111]
	v_mfma_f32_16x16x32_bf16 v[104:107], v[160:163], v[172:175], v[104:107]
	v_mfma_f32_16x16x32_bf16 v[100:103], v[164:167], v[172:175], v[100:103]
	global_load_lds_dwordx4 v[170:171], off
	v_lshl_add_u64 v[170:171], v[168:169], 0, s[8:9]
	s_mov_b32 m0, s93
	s_mov_b64 s[8:9], 0x19e8b080
	s_waitcnt lgkmcnt(5)
	v_mfma_f32_16x16x32_bf16 v[80:83], v[128:131], v[176:179], v[80:83]
	v_lshl_add_u64 v[168:169], v[168:169], 0, s[8:9]
	s_mov_b64 s[8:9], 0x245080
	v_mfma_f32_16x16x32_bf16 v[92:95], v[156:159], v[176:179], v[92:95]
	v_mfma_f32_16x16x32_bf16 v[88:91], v[160:163], v[176:179], v[88:91]
	v_mfma_f32_16x16x32_bf16 v[84:87], v[164:167], v[176:179], v[84:87]
	global_load_lds_dwordx4 v[170:171], off
	s_mov_b32 m0, s94
	s_waitcnt lgkmcnt(4)
	v_mfma_f32_16x16x32_bf16 v[64:67], v[128:131], v[180:183], v[64:67]
	v_mfma_f32_16x16x32_bf16 v[76:79], v[156:159], v[180:183], v[76:79]
	v_mfma_f32_16x16x32_bf16 v[72:75], v[160:163], v[180:183], v[72:75]
	v_mfma_f32_16x16x32_bf16 v[68:71], v[164:167], v[180:183], v[68:71]
	global_load_lds_dwordx4 v[168:169], off
	s_mov_b32 m0, s89
	s_waitcnt lgkmcnt(3)
	v_mfma_f32_16x16x32_bf16 v[48:51], v[128:131], v[184:187], v[48:51]
	v_mfma_f32_16x16x32_bf16 v[60:63], v[156:159], v[184:187], v[60:63]
	v_mfma_f32_16x16x32_bf16 v[56:59], v[160:163], v[184:187], v[56:59]
	v_mfma_f32_16x16x32_bf16 v[52:55], v[164:167], v[184:187], v[52:55]
	s_waitcnt lgkmcnt(2)
	v_mfma_f32_16x16x32_bf16 v[32:35], v[128:131], v[188:191], v[32:35]
	v_mfma_f32_16x16x32_bf16 v[44:47], v[156:159], v[188:191], v[44:47]
	v_mfma_f32_16x16x32_bf16 v[40:43], v[160:163], v[188:191], v[40:43]
	v_mfma_f32_16x16x32_bf16 v[36:39], v[164:167], v[188:191], v[36:39]
	s_waitcnt lgkmcnt(1)
	v_mfma_f32_16x16x32_bf16 v[12:15], v[128:131], v[192:195], v[12:15]
	v_mfma_f32_16x16x32_bf16 v[24:27], v[156:159], v[192:195], v[24:27]
	v_mfma_f32_16x16x32_bf16 v[20:23], v[160:163], v[192:195], v[20:23]
	v_mfma_f32_16x16x32_bf16 v[16:19], v[164:167], v[192:195], v[16:19]
	s_waitcnt lgkmcnt(0)
	v_mfma_f32_16x16x32_bf16 v[0:3], v[128:131], v[196:199], v[0:3]
	v_mfma_f32_16x16x32_bf16 v[8:11], v[156:159], v[196:199], v[8:11]
	v_mfma_f32_16x16x32_bf16 v[4:7], v[160:163], v[196:199], v[4:7]
	v_mfma_f32_16x16x32_bf16 v[28:31], v[164:167], v[196:199], v[28:31]
	ds_read_b128 v[128:131], v150 offset:32768
	ds_read_b128 v[168:171], v151
	ds_read_b128 v[156:159], v150 offset:34816
	ds_read_b128 v[160:163], v150 offset:36864
	ds_read_b128 v[164:167], v150 offset:38912
	ds_read_b128 v[172:175], v151 offset:2048
	ds_read_b128 v[176:179], v151 offset:4096
	ds_read_b128 v[180:183], v151 offset:6144
	ds_read_b128 v[184:187], v151 offset:8192
	ds_read_b128 v[188:191], v151 offset:10240
	ds_read_b128 v[192:195], v151 offset:12288
	ds_read_b128 v[196:199], v151 offset:14336
	s_waitcnt lgkmcnt(10)
	v_mfma_f32_16x16x32_bf16 v[112:115], v[128:131], v[168:171], v[112:115]
	s_waitcnt lgkmcnt(9)
	v_mfma_f32_16x16x32_bf16 v[124:127], v[156:159], v[168:171], v[124:127]
	s_waitcnt lgkmcnt(8)
	v_mfma_f32_16x16x32_bf16 v[120:123], v[160:163], v[168:171], v[120:123]
	s_waitcnt lgkmcnt(7)
	v_mfma_f32_16x16x32_bf16 v[116:119], v[164:167], v[168:171], v[116:119]
	v_lshl_add_u64 v[168:169], v[140:141], 0, v[132:133]
	v_lshl_add_u64 v[170:171], v[168:169], 0, s[8:9]
	s_mov_b64 s[8:9], 0x287080
	global_load_lds_dwordx4 v[170:171], off
	v_lshl_add_u64 v[170:171], v[168:169], 0, s[8:9]
	s_mov_b32 m0, s95
	s_waitcnt lgkmcnt(6)
	v_mfma_f32_16x16x32_bf16 v[96:99], v[128:131], v[172:175], v[96:99]
	s_cselect_b64 s[8:9], -1, 0
	s_and_b64 vcc, s[8:9], exec
	s_cselect_b32 s6, s7, s18
	v_mfma_f32_16x16x32_bf16 v[108:111], v[156:159], v[172:175], v[108:111]
	s_lshl_b32 s18, s6, 7
	v_lshl_add_u64 v[140:141], v[140:141], 0, s[34:35]
	s_mov_b32 s6, s7
	v_mfma_f32_16x16x32_bf16 v[104:107], v[160:163], v[172:175], v[104:107]
	v_mfma_f32_16x16x32_bf16 v[100:103], v[164:167], v[172:175], v[100:103]
	global_load_lds_dwordx4 v[170:171], off
	v_lshl_add_u64 v[170:171], v[168:169], 0, s[28:29]
	s_mov_b32 m0, s96
	s_waitcnt lgkmcnt(5)
; #define G3_LDA(buf, kt, i) __builtin_amdgcn_global_load_lds((const unsigned*)(ga + (size_t)((i) * 64) * lda + (kt) * 64), (lds_u32*)(sdst + (buf) * STAGE + (i) * 8192), 16, 0, 0)
; #define G3_LDB(buf, kt, i) __builtin_amdgcn_global_load_lds((const unsigned*)(gb + (size_t)((i) * 64) * ldb + (kt) * 64), (lds_u32*)(sdst + (buf) * STAGE + B_OFF + (i) * 8192), 16, 0, 0)
; DI void gemm3_mainloop(const int wave8, const int lane, const bf16_t* __restrict__ A, int lda, const bf16_t* __restrict__ Bt, int ldb, int K,
;                        unsigned char* smem, f32x4 (&acc)[8][4]) {
;     ...
;     asm volatile("s_waitcnt vmcnt(0)" ::: "memory");
;     G3_LDA(0, 0, 0); G3_LDA(0, 0, 1); G3_LDA(0, 0, 2); G3_LDA(0, 0, 3); G3_LDB(0, 0, 0); G3_LDB(0, 0, 1); G3_LDB(0, 0, 2); G3_LDB(0, 0, 3);
;     asm volatile("s_waitcnt vmcnt(0)" ::: "memory");
;     __builtin_amdgcn_s_barrier();
;     for (int kt = 0; kt < nk; kt += 2) { G3_STEP(0, 1, kt); G3_STEP(1, 0, kt + 1); }
	v_mfma_f32_16x16x32_bf16 v[80:83], v[128:131], v[176:179], v[80:83]
	v_lshl_add_u64 v[168:169], v[168:169], 0, s[30:31]
	v_mfma_f32_16x16x32_bf16 v[92:95], v[156:159], v[176:179], v[92:95]
	v_mfma_f32_16x16x32_bf16 v[88:91], v[160:163], v[176:179], v[88:91]
	v_mfma_f32_16x16x32_bf16 v[84:87], v[164:167], v[176:179], v[84:87]
	global_load_lds_dwordx4 v[170:171], off
	s_mov_b32 m0, s97
	s_waitcnt lgkmcnt(4)
	v_mfma_f32_16x16x32_bf16 v[64:67], v[128:131], v[180:183], v[64:67]
	v_mfma_f32_16x16x32_bf16 v[76:79], v[156:159], v[180:183], v[76:79]
	v_mfma_f32_16x16x32_bf16 v[72:75], v[160:163], v[180:183], v[72:75]
	v_mfma_f32_16x16x32_bf16 v[68:71], v[164:167], v[180:183], v[68:71]
	global_load_lds_dwordx4 v[168:169], off
	s_waitcnt lgkmcnt(3)
	v_mfma_f32_16x16x32_bf16 v[48:51], v[128:131], v[184:187], v[48:51]
	s_mov_b32 m0, s0
	v_mfma_f32_16x16x32_bf16 v[60:63], v[156:159], v[184:187], v[60:63]
	v_mfma_f32_16x16x32_bf16 v[56:59], v[160:163], v[184:187], v[56:59]
	v_mfma_f32_16x16x32_bf16 v[52:55], v[164:167], v[184:187], v[52:55]
	s_waitcnt lgkmcnt(2)
	v_mfma_f32_16x16x32_bf16 v[32:35], v[128:131], v[188:191], v[32:35]
	v_mfma_f32_16x16x32_bf16 v[44:47], v[156:159], v[188:191], v[44:47]
	v_mfma_f32_16x16x32_bf16 v[40:43], v[160:163], v[188:191], v[40:43]
	v_mfma_f32_16x16x32_bf16 v[36:39], v[164:167], v[188:191], v[36:39]
	s_waitcnt lgkmcnt(1)
	v_mfma_f32_16x16x32_bf16 v[12:15], v[128:131], v[192:195], v[12:15]
	v_mfma_f32_16x16x32_bf16 v[24:27], v[156:159], v[192:195], v[24:27]
	v_mfma_f32_16x16x32_bf16 v[20:23], v[160:163], v[192:195], v[20:23]
	v_mfma_f32_16x16x32_bf16 v[16:19], v[164:167], v[192:195], v[16:19]
	s_waitcnt lgkmcnt(0)
	v_mfma_f32_16x16x32_bf16 v[0:3], v[128:131], v[196:199], v[0:3]
	s_waitcnt vmcnt(0)
	s_barrier
	v_mfma_f32_16x16x32_bf16 v[8:11], v[156:159], v[196:199], v[8:11]
	v_mfma_f32_16x16x32_bf16 v[4:7], v[160:163], v[196:199], v[4:7]
	v_mfma_f32_16x16x32_bf16 v[28:31], v[164:167], v[196:199], v[28:31]
	ds_read_b128 v[128:131], v152
	ds_read_b128 v[168:171], v153
	ds_read_b128 v[156:159], v152 offset:2048
	ds_read_b128 v[160:163], v152 offset:4096
	ds_read_b128 v[164:167], v152 offset:6144
	ds_read_b128 v[172:175], v153 offset:2048
	ds_read_b128 v[176:179], v153 offset:4096
	ds_read_b128 v[180:183], v153 offset:6144
	ds_read_b128 v[184:187], v153 offset:8192
	ds_read_b128 v[188:191], v153 offset:10240
	ds_read_b128 v[192:195], v153 offset:12288
	ds_read_b128 v[196:199], v153 offset:14336
	s_waitcnt lgkmcnt(10)
	v_mfma_f32_16x16x32_bf16 v[112:115], v[128:131], v[168:171], v[112:115]
	s_waitcnt lgkmcnt(9)
	v_mfma_f32_16x16x32_bf16 v[124:127], v[156:159], v[168:171], v[124:127]
	s_waitcnt lgkmcnt(8)
	v_mfma_f32_16x16x32_bf16 v[120:123], v[160:163], v[168:171], v[120:123]
	s_waitcnt lgkmcnt(7)
	v_mfma_f32_16x16x32_bf16 v[116:119], v[164:167], v[168:171], v[116:119]
	v_lshl_add_u64 v[168:169], v[134:135], 0, s[18:19]
	global_load_lds_dwordx4 v[168:169], off
	v_lshl_add_u64 v[170:171], v[168:169], 0, s[22:23]
	s_mov_b32 m0, s55
	s_waitcnt lgkmcnt(6)
	v_mfma_f32_16x16x32_bf16 v[96:99], v[128:131], v[172:175], v[96:99]
	v_mfma_f32_16x16x32_bf16 v[108:111], v[156:159], v[172:175], v[108:111]
	v_mfma_f32_16x16x32_bf16 v[104:107], v[160:163], v[172:175], v[104:107]
	v_mfma_f32_16x16x32_bf16 v[100:103], v[164:167], v[172:175], v[100:103]
	global_load_lds_dwordx4 v[170:171], off
	v_lshl_add_u64 v[170:171], v[168:169], 0, s[24:25]
	s_mov_b32 m0, s87
	s_waitcnt lgkmcnt(5)
	v_mfma_f32_16x16x32_bf16 v[80:83], v[128:131], v[176:179], v[80:83]
	v_lshl_add_u64 v[168:169], v[168:169], 0, s[26:27]
	v_mfma_f32_16x16x32_bf16 v[92:95], v[156:159], v[176:179], v[92:95]
	v_mfma_f32_16x16x32_bf16 v[88:91], v[160:163], v[176:179], v[88:91]
	v_mfma_f32_16x16x32_bf16 v[84:87], v[164:167], v[176:179], v[84:87]
	global_load_lds_dwordx4 v[170:171], off
	s_mov_b32 m0, s69
	s_waitcnt lgkmcnt(4)
	v_mfma_f32_16x16x32_bf16 v[64:67], v[128:131], v[180:183], v[64:67]
	v_mfma_f32_16x16x32_bf16 v[76:79], v[156:159], v[180:183], v[76:79]
	v_mfma_f32_16x16x32_bf16 v[72:75], v[160:163], v[180:183], v[72:75]
	v_mfma_f32_16x16x32_bf16 v[68:71], v[164:167], v[180:183], v[68:71]
	global_load_lds_dwordx4 v[168:169], off
	s_mov_b32 m0, s68
	s_waitcnt lgkmcnt(3)
	v_mfma_f32_16x16x32_bf16 v[48:51], v[128:131], v[184:187], v[48:51]
	v_mfma_f32_16x16x32_bf16 v[60:63], v[156:159], v[184:187], v[60:63]
	v_mfma_f32_16x16x32_bf16 v[56:59], v[160:163], v[184:187], v[56:59]
	v_mfma_f32_16x16x32_bf16 v[52:55], v[164:167], v[184:187], v[52:55]
	s_waitcnt lgkmcnt(2)
	v_mfma_f32_16x16x32_bf16 v[32:35], v[128:131], v[188:191], v[32:35]
	v_mfma_f32_16x16x32_bf16 v[44:47], v[156:159], v[188:191], v[44:47]
	v_mfma_f32_16x16x32_bf16 v[40:43], v[160:163], v[188:191], v[40:43]
	v_mfma_f32_16x16x32_bf16 v[36:39], v[164:167], v[188:191], v[36:39]
	s_waitcnt lgkmcnt(1)
	v_mfma_f32_16x16x32_bf16 v[12:15], v[128:131], v[192:195], v[12:15]
	v_mfma_f32_16x16x32_bf16 v[24:27], v[156:159], v[192:195], v[24:27]
	v_mfma_f32_16x16x32_bf16 v[20:23], v[160:163], v[192:195], v[20:23]
	v_mfma_f32_16x16x32_bf16 v[16:19], v[164:167], v[192:195], v[16:19]
	s_waitcnt lgkmcnt(0)
	v_mfma_f32_16x16x32_bf16 v[0:3], v[128:131], v[196:199], v[0:3]
	v_mfma_f32_16x16x32_bf16 v[8:11], v[156:159], v[196:199], v[8:11]
	v_mfma_f32_16x16x32_bf16 v[4:7], v[160:163], v[196:199], v[4:7]
	v_mfma_f32_16x16x32_bf16 v[28:31], v[164:167], v[196:199], v[28:31]
	ds_read_b128 v[156:159], v154
	ds_read_b128 v[168:171], v155
	ds_read_b128 v[160:163], v154 offset:2048
	ds_read_b128 v[164:167], v154 offset:4096
	ds_read_b128 v[128:131], v154 offset:6144
	ds_read_b128 v[172:175], v155 offset:2048
	ds_read_b128 v[176:179], v155 offset:4096
	ds_read_b128 v[180:183], v155 offset:6144
	ds_read_b128 v[184:187], v155 offset:8192
	ds_read_b128 v[188:191], v155 offset:10240
	ds_read_b128 v[192:195], v155 offset:12288
	ds_read_b128 v[196:199], v155 offset:14336
	s_waitcnt lgkmcnt(10)
; DI unsigned pk2(float a, float b) { f2_t v = {a, b}; bf2_t r = __builtin_convertvector(v, bf2_t); return __builtin_bit_cast(unsigned, r); }
; #define G3_LDA(buf, kt, i) __builtin_amdgcn_global_load_lds((const unsigned*)(ga + (size_t)((i) * 64) * lda + (kt) * 64), (lds_u32*)(sdst + (buf) * STAGE + (i) * 8192), 16, 0, 0)
; #define G3_LDB(buf, kt, i) __builtin_amdgcn_global_load_lds((const unsigned*)(gb + (size_t)((i) * 64) * ldb + (kt) * 64), (lds_u32*)(sdst + (buf) * STAGE + B_OFF + (i) * 8192), 16, 0, 0)
; DI void gemm3_mainloop(const int wave8, const int lane, const bf16_t* __restrict__ A, int lda, const bf16_t* __restrict__ Bt, int ldb, int K,
;                        unsigned char* smem, f32x4 (&acc)[8][4]) {
;     ...
;     asm volatile("s_waitcnt vmcnt(0)" ::: "memory");
;     G3_LDA(0, 0, 0); G3_LDA(0, 0, 1); G3_LDA(0, 0, 2); G3_LDA(0, 0, 3); G3_LDB(0, 0, 0); G3_LDB(0, 0, 1); G3_LDB(0, 0, 2); G3_LDB(0, 0, 3);
;     asm volatile("s_waitcnt vmcnt(0)" ::: "memory");
;     __builtin_amdgcn_s_barrier();
;     for (int kt = 0; kt < nk; kt += 2) { G3_STEP(0, 1, kt); G3_STEP(1, 0, kt + 1); }
; DI void phase1(const Params& p, unsigned char* smem) {
;     ...
;         const int c128 = nt * 2 + (wn >> 1);
;         if (c128 >= 47) return;
;         bf16_t* dst; int ld, c0;
;         if (c128 < 23) { dst = pa; ld = LDPA; c0 = c128 * 128; } else { dst = pb; ld = LDPB; c0 = (c128 - 23) * 128; }
; #pragma unroll
;         for (int i = 0; i < 8; ++i) {
;             const int m = mt * 256 + wm * 128 + i * 16 + fr;
;             float ss = 0.f;
; #pragma unroll
;             for (int j = 0; j < 4; ++j) {
;                 const f32x4 v = acc[i][j];
;                 ss += v.x * v.x + v.y * v.y + v.z * v.z + v.w * v.w;
;                 u32x2 o; o.x = pk2(v.x, v.y); o.y = pk2(v.z, v.w);
;                 *(u32x2*)(dst + (size_t)m * ld + c0 + (wn & 1) * 64 + j * 16 + fq * 4) = o;
;             }
;             if (c128 < 6) {
;                 ss += __shfl_xor(ss, 16); ss += __shfl_xor(ss, 32);
;                 if (fq == 0) atomicAdd(ssq + (c128 < 4 ? 0 : T_) + m, ss);
	v_mfma_f32_16x16x32_bf16 v[112:115], v[156:159], v[168:171], v[112:115]
	s_waitcnt lgkmcnt(9)
	v_mfma_f32_16x16x32_bf16 v[124:127], v[160:163], v[168:171], v[124:127]
	s_waitcnt lgkmcnt(8)
	v_mfma_f32_16x16x32_bf16 v[120:123], v[164:167], v[168:171], v[120:123]
	s_waitcnt lgkmcnt(7)
	v_mfma_f32_16x16x32_bf16 v[116:119], v[128:131], v[168:171], v[116:119]
	v_lshl_add_u64 v[168:169], v[136:137], 0, s[18:19]
	global_load_lds_dwordx4 v[168:169], off
	v_lshl_add_u64 v[170:171], v[168:169], 0, s[22:23]
	s_mov_b32 m0, s39
	s_waitcnt lgkmcnt(6)
	v_mfma_f32_16x16x32_bf16 v[96:99], v[156:159], v[172:175], v[96:99]
	v_mfma_f32_16x16x32_bf16 v[108:111], v[160:163], v[172:175], v[108:111]
	v_mfma_f32_16x16x32_bf16 v[104:107], v[164:167], v[172:175], v[104:107]
	v_mfma_f32_16x16x32_bf16 v[100:103], v[128:131], v[172:175], v[100:103]
	global_load_lds_dwordx4 v[170:171], off
	v_lshl_add_u64 v[170:171], v[168:169], 0, s[24:25]
	s_mov_b32 m0, s38
	s_waitcnt lgkmcnt(5)
	v_mfma_f32_16x16x32_bf16 v[80:83], v[156:159], v[176:179], v[80:83]
	v_lshl_add_u64 v[168:169], v[168:169], 0, s[26:27]
	v_mfma_f32_16x16x32_bf16 v[92:95], v[160:163], v[176:179], v[92:95]
	v_mfma_f32_16x16x32_bf16 v[88:91], v[164:167], v[176:179], v[88:91]
	v_mfma_f32_16x16x32_bf16 v[84:87], v[128:131], v[176:179], v[84:87]
	global_load_lds_dwordx4 v[170:171], off
	s_mov_b32 m0, s1
	s_waitcnt lgkmcnt(4)
	v_mfma_f32_16x16x32_bf16 v[64:67], v[156:159], v[180:183], v[64:67]
	v_mfma_f32_16x16x32_bf16 v[76:79], v[160:163], v[180:183], v[76:79]
	v_mfma_f32_16x16x32_bf16 v[72:75], v[164:167], v[180:183], v[72:75]
	v_mfma_f32_16x16x32_bf16 v[68:71], v[128:131], v[180:183], v[68:71]
	global_load_lds_dwordx4 v[168:169], off
	s_waitcnt lgkmcnt(3)
	v_mfma_f32_16x16x32_bf16 v[48:51], v[156:159], v[184:187], v[48:51]
	v_mfma_f32_16x16x32_bf16 v[60:63], v[160:163], v[184:187], v[60:63]
	v_mfma_f32_16x16x32_bf16 v[56:59], v[164:167], v[184:187], v[56:59]
	v_mfma_f32_16x16x32_bf16 v[52:55], v[128:131], v[184:187], v[52:55]
	s_waitcnt lgkmcnt(2)
	v_mfma_f32_16x16x32_bf16 v[32:35], v[156:159], v[188:191], v[32:35]
	v_mfma_f32_16x16x32_bf16 v[44:47], v[160:163], v[188:191], v[44:47]
	v_mfma_f32_16x16x32_bf16 v[40:43], v[164:167], v[188:191], v[40:43]
	v_mfma_f32_16x16x32_bf16 v[36:39], v[128:131], v[188:191], v[36:39]
	s_waitcnt lgkmcnt(1)
	v_mfma_f32_16x16x32_bf16 v[12:15], v[156:159], v[192:195], v[12:15]
	v_mfma_f32_16x16x32_bf16 v[24:27], v[160:163], v[192:195], v[24:27]
	v_mfma_f32_16x16x32_bf16 v[20:23], v[164:167], v[192:195], v[20:23]
	v_mfma_f32_16x16x32_bf16 v[16:19], v[128:131], v[192:195], v[16:19]
	s_waitcnt lgkmcnt(0)
	v_mfma_f32_16x16x32_bf16 v[0:3], v[156:159], v[196:199], v[0:3]
	s_waitcnt vmcnt(0)
	s_barrier
	v_mfma_f32_16x16x32_bf16 v[8:11], v[160:163], v[196:199], v[8:11]
	v_mfma_f32_16x16x32_bf16 v[4:7], v[164:167], v[196:199], v[4:7]
	v_mfma_f32_16x16x32_bf16 v[28:31], v[128:131], v[196:199], v[28:31]
	s_cbranch_vccnz .LBB0_90
	s_lshl_b32 s5, s5, 1
	s_or_b32 s36, s5, s44
	s_cmp_gt_i32 s36, 46
	s_cbranch_scc1 .LBB0_88
	s_lshl_b32 s5, s36, 7
	s_add_i32 s6, s5, 0xfffff480
	s_cmp_lt_i32 s36, 23
	s_cselect_b32 s6, s5, s6
	s_cselect_b32 s5, s48, 0xddc5000
	s_cselect_b32 s75, s46, 0xc00
	s_add_u32 s8, s72, s5
	s_addc_u32 s9, s73, 0
	s_lshl_b32 s4, s4, 8
	s_add_i32 s4, s4, s54
	s_ashr_i32 s7, s6, 31
	v_and_or_b32 v130, v147, 15, s4
	s_lshl_b64 s[4:5], s[6:7], 1
	s_add_u32 s4, s8, s4
	s_addc_u32 s5, s9, s5
	s_add_u32 s4, s4, s49
	s_addc_u32 s5, s5, 0
	v_lshlrev_b32_e32 v132, 3, v145
	v_lshl_add_u64 v[128:129], s[4:5], 0, v[132:133]
	v_mov_b32_e32 v132, v130
	v_mad_u64_u32 v[130:131], s[4:5], s75, v130, 0
	v_lshl_add_u64 v[130:131], v[130:131], 1, v[128:129]
	v_cvt_pk_bf16_f32 v134, v112, v113
	v_cvt_pk_bf16_f32 v135, v114, v115
	s_cmp_lt_i32 s36, 6
	global_store_dwordx2 v[130:131], v[134:135], off
	v_cvt_pk_bf16_f32 v134, v124, v125
	v_cvt_pk_bf16_f32 v135, v126, v127
	s_cselect_b64 s[6:7], -1, 0
	s_cmp_lt_i32 s36, 4
	global_store_dwordx2 v[130:131], v[134:135], off offset:32
	v_cvt_pk_bf16_f32 v134, v120, v121
	v_cvt_pk_bf16_f32 v135, v122, v123
	s_cselect_b32 s18, 0, 0x8000
	s_cmp_gt_i32 s36, 5
	v_cmp_gt_u32_e64 s[8:9], 16, v146
	global_store_dwordx2 v[130:131], v[134:135], off offset:64
	v_cvt_pk_bf16_f32 v134, v116, v117
	v_cvt_pk_bf16_f32 v135, v118, v119
	global_store_dwordx2 v[130:131], v[134:135], off offset:96
	s_cbranch_scc1 .LBB0_96
	v_mul_f32_e32 v130, v113, v113
	v_mul_f32_e32 v125, v125, v125
	v_fmac_f32_e32 v130, v112, v112
	v_fmac_f32_e32 v125, v124, v124
	v_mul_f32_e32 v121, v121, v121
	v_fmac_f32_e32 v130, v114, v114
	v_fmac_f32_e32 v125, v126, v126
	v_fmac_f32_e32 v121, v120, v120
	v_mul_f32_e32 v117, v117, v117
	v_fmac_f32_e32 v130, v115, v115
	v_fmac_f32_e32 v125, v127, v127
	v_fmac_f32_e32 v121, v122, v122
	v_fmac_f32_e32 v117, v116, v116
	v_add_f32_e32 v124, v130, v125
	v_fmac_f32_e32 v121, v123, v123
	v_fmac_f32_e32 v117, v118, v118
	v_add_f32_e32 v120, v124, v121
	v_fmac_f32_e32 v117, v119, v119
	v_add_f32_e32 v116, v120, v117
	ds_bpermute_b32 v117, v144, v116
	s_waitcnt lgkmcnt(0)
	v_add_f32_e32 v116, v116, v117
	ds_bpermute_b32 v117, v241, v116
	s_and_saveexec_b64 s[4:5], s[8:9]
	s_cbranch_execz .LBB0_95
	s_lshl_b32 s37, s18, 2
	s_add_u32 s76, s12, s37
	s_addc_u32 s77, s13, 0
	s_waitcnt lgkmcnt(0)
	v_add_f32_e32 v118, v116, v117
	v_lshl_add_u64 v[116:117], v[132:133], 2, s[76:77]
	v_add_f32_e32 v118, 0x45400000, v118
	v_subrev_f32_e32 v118, 0x45400000, v118
	global_atomic_add_f32 v[116:117], v118, off

; #define G3_LDA(buf, kt, i) __builtin_amdgcn_global_load_lds((const unsigned*)(ga + (size_t)((i) * 64) * lda + (kt) * 64), (lds_u32*)(sdst + (buf) * STAGE + (i) * 8192), 16, 0, 0)
; #define G3_LDB(buf, kt, i) __builtin_amdgcn_global_load_lds((const unsigned*)(gb + (size_t)((i) * 64) * ldb + (kt) * 64), (lds_u32*)(sdst + (buf) * STAGE + B_OFF + (i) * 8192), 16, 0, 0)
; DI void gemm3_mainloop(const int wave8, const int lane, const bf16_t* __restrict__ A, int lda, const bf16_t* __restrict__ Bt, int ldb, int K,
;                        unsigned char* smem, f32x4 (&acc)[8][4]) {
;     ...
;     asm volatile("s_waitcnt vmcnt(0)" ::: "memory");
;     G3_LDA(0, 0, 0); G3_LDA(0, 0, 1); G3_LDA(0, 0, 2); G3_LDA(0, 0, 3); G3_LDB(0, 0, 0); G3_LDB(0, 0, 1); G3_LDB(0, 0, 2); G3_LDB(0, 0, 3);
;     asm volatile("s_waitcnt vmcnt(0)" ::: "memory");
;     __builtin_amdgcn_s_barrier();
;     for (int kt = 0; kt < nk; kt += 2) { G3_STEP(0, 1, kt); G3_STEP(1, 0, kt + 1); }
.LBB0_503:
	ds_read_b128 v[148:151], v139 offset:32768
	ds_read_b128 v[164:167], v140
	ds_read_b128 v[152:155], v139 offset:34816
	ds_read_b128 v[156:159], v139 offset:36864
	ds_read_b128 v[160:163], v139 offset:38912
	ds_read_b128 v[168:171], v140 offset:2048
	ds_read_b128 v[172:175], v140 offset:4096
	ds_read_b128 v[176:179], v140 offset:6144
	ds_read_b128 v[180:183], v140 offset:8192
	ds_read_b128 v[184:187], v140 offset:10240
	ds_read_b128 v[188:191], v140 offset:12288
	ds_read_b128 v[192:195], v140 offset:14336
	v_lshl_add_u64 v[196:197], v[134:135], 0, v[128:129]
	s_mov_b32 m0, s88
	s_waitcnt lgkmcnt(10)
	v_mfma_f32_16x16x32_bf16 v[124:127], v[148:151], v[164:167], v[124:127]
	s_add_i32 s50, s2, 1
	s_add_i32 s47, s2, 2
	s_cmp_lt_u32 s2, 30
	s_waitcnt lgkmcnt(9)
	v_mfma_f32_16x16x32_bf16 v[120:123], v[152:155], v[164:167], v[120:123]
	s_cselect_b64 s[48:49], -1, 0
	s_and_b64 vcc, s[48:49], exec
	s_cselect_b32 s2, s47, s50
	s_waitcnt lgkmcnt(8)
	v_mfma_f32_16x16x32_bf16 v[116:119], v[156:159], v[164:167], v[116:119]
	s_lshl_b32 s2, s2, 7
	v_lshl_add_u64 v[134:135], v[134:135], 0, s[26:27]
	s_waitcnt lgkmcnt(7)
	v_mfma_f32_16x16x32_bf16 v[112:115], v[160:163], v[164:167], v[112:115]
	v_lshl_add_u64 v[164:165], v[196:197], 0, s[10:11]
	global_load_lds_dwordx4 v[164:165], off
	v_lshl_add_u64 v[164:165], v[196:197], 0, s[12:13]
	s_mov_b32 m0, s92
	s_waitcnt lgkmcnt(6)
	v_mfma_f32_16x16x32_bf16 v[108:111], v[148:151], v[168:171], v[108:111]
	v_mfma_f32_16x16x32_bf16 v[104:107], v[152:155], v[168:171], v[104:107]
	v_mfma_f32_16x16x32_bf16 v[100:103], v[156:159], v[168:171], v[100:103]
	v_mfma_f32_16x16x32_bf16 v[96:99], v[160:163], v[168:171], v[96:99]
	global_load_lds_dwordx4 v[164:165], off
	v_lshl_add_u64 v[164:165], v[196:197], 0, s[14:15]
	s_mov_b32 m0, s93
	s_waitcnt lgkmcnt(5)
	v_mfma_f32_16x16x32_bf16 v[92:95], v[148:151], v[172:175], v[92:95]
	v_mfma_f32_16x16x32_bf16 v[88:91], v[152:155], v[172:175], v[88:91]
	v_mfma_f32_16x16x32_bf16 v[84:87], v[156:159], v[172:175], v[84:87]
	v_mfma_f32_16x16x32_bf16 v[80:83], v[160:163], v[172:175], v[80:83]
	global_load_lds_dwordx4 v[164:165], off
	v_lshl_add_u64 v[164:165], v[196:197], 0, s[16:17]
	s_mov_b32 m0, s94
	s_waitcnt lgkmcnt(4)
	v_mfma_f32_16x16x32_bf16 v[76:79], v[148:151], v[176:179], v[76:79]
	v_lshl_add_u64 v[196:197], v[136:137], 0, v[128:129]
	v_lshl_add_u64 v[198:199], v[196:197], 0, s[18:19]
	v_lshl_add_u64 v[136:137], v[136:137], 0, s[26:27]
	v_mfma_f32_16x16x32_bf16 v[72:75], v[152:155], v[176:179], v[72:75]
	v_mfma_f32_16x16x32_bf16 v[68:71], v[156:159], v[176:179], v[68:71]
	v_mfma_f32_16x16x32_bf16 v[64:67], v[160:163], v[176:179], v[64:67]
	global_load_lds_dwordx4 v[164:165], off
	s_mov_b32 m0, s89
	s_waitcnt lgkmcnt(3)
	v_mfma_f32_16x16x32_bf16 v[60:63], v[148:151], v[180:183], v[60:63]
	v_mfma_f32_16x16x32_bf16 v[56:59], v[152:155], v[180:183], v[56:59]
	v_mfma_f32_16x16x32_bf16 v[52:55], v[156:159], v[180:183], v[52:55]
	v_mfma_f32_16x16x32_bf16 v[48:51], v[160:163], v[180:183], v[48:51]
	s_waitcnt lgkmcnt(2)
	v_mfma_f32_16x16x32_bf16 v[44:47], v[148:151], v[184:187], v[44:47]
	v_mfma_f32_16x16x32_bf16 v[40:43], v[152:155], v[184:187], v[40:43]
	v_mfma_f32_16x16x32_bf16 v[36:39], v[156:159], v[184:187], v[36:39]
	v_mfma_f32_16x16x32_bf16 v[28:31], v[160:163], v[184:187], v[28:31]
	s_waitcnt lgkmcnt(1)
	v_mfma_f32_16x16x32_bf16 v[24:27], v[148:151], v[188:191], v[24:27]
	v_mfma_f32_16x16x32_bf16 v[20:23], v[152:155], v[188:191], v[20:23]
	v_mfma_f32_16x16x32_bf16 v[16:19], v[156:159], v[188:191], v[16:19]
	v_mfma_f32_16x16x32_bf16 v[12:15], v[160:163], v[188:191], v[12:15]
	s_waitcnt lgkmcnt(0)
	v_mfma_f32_16x16x32_bf16 v[8:11], v[148:151], v[192:195], v[8:11]
	v_mfma_f32_16x16x32_bf16 v[4:7], v[152:155], v[192:195], v[4:7]
	v_mfma_f32_16x16x32_bf16 v[0:3], v[156:159], v[192:195], v[0:3]
	v_mfma_f32_16x16x32_bf16 v[32:35], v[160:163], v[192:195], v[32:35]
	ds_read_b128 v[148:151], v141 offset:32768
	ds_read_b128 v[164:167], v142
	ds_read_b128 v[152:155], v141 offset:34816
	ds_read_b128 v[156:159], v141 offset:36864
	ds_read_b128 v[160:163], v141 offset:38912
	ds_read_b128 v[168:171], v142 offset:2048
	ds_read_b128 v[172:175], v142 offset:4096
	ds_read_b128 v[176:179], v142 offset:6144
	ds_read_b128 v[180:183], v142 offset:8192
	ds_read_b128 v[184:187], v142 offset:10240
	ds_read_b128 v[188:191], v142 offset:12288
	ds_read_b128 v[192:195], v142 offset:14336
	s_waitcnt lgkmcnt(10)
	v_mfma_f32_16x16x32_bf16 v[124:127], v[148:151], v[164:167], v[124:127]
	s_waitcnt lgkmcnt(9)
	v_mfma_f32_16x16x32_bf16 v[120:123], v[152:155], v[164:167], v[120:123]
	s_waitcnt lgkmcnt(8)
	v_mfma_f32_16x16x32_bf16 v[116:119], v[156:159], v[164:167], v[116:119]
	s_waitcnt lgkmcnt(7)
	v_mfma_f32_16x16x32_bf16 v[112:115], v[160:163], v[164:167], v[112:115]
	global_load_lds_dwordx4 v[198:199], off
	v_lshl_add_u64 v[164:165], v[196:197], 0, s[20:21]
	s_mov_b32 m0, s95
	s_waitcnt lgkmcnt(6)
	v_mfma_f32_16x16x32_bf16 v[108:111], v[148:151], v[168:171], v[108:111]
	v_mfma_f32_16x16x32_bf16 v[104:107], v[152:155], v[168:171], v[104:107]
	v_mfma_f32_16x16x32_bf16 v[100:103], v[156:159], v[168:171], v[100:103]
	v_mfma_f32_16x16x32_bf16 v[96:99], v[160:163], v[168:171], v[96:99]
	global_load_lds_dwordx4 v[164:165], off
	v_lshl_add_u64 v[164:165], v[196:197], 0, s[22:23]
	s_mov_b32 m0, s96
	s_waitcnt lgkmcnt(5)
	v_mfma_f32_16x16x32_bf16 v[92:95], v[148:151], v[172:175], v[92:95]
	v_mfma_f32_16x16x32_bf16 v[88:91], v[152:155], v[172:175], v[88:91]
	v_mfma_f32_16x16x32_bf16 v[84:87], v[156:159], v[172:175], v[84:87]
	v_mfma_f32_16x16x32_bf16 v[80:83], v[160:163], v[172:175], v[80:83]
	global_load_lds_dwordx4 v[164:165], off
	v_lshl_add_u64 v[164:165], v[196:197], 0, s[24:25]
	s_mov_b32 m0, s97
	s_waitcnt lgkmcnt(4)
; #define G3_LDA(buf, kt, i) __builtin_amdgcn_global_load_lds((const unsigned*)(ga + (size_t)((i) * 64) * lda + (kt) * 64), (lds_u32*)(sdst + (buf) * STAGE + (i) * 8192), 16, 0, 0)
; #define G3_LDB(buf, kt, i) __builtin_amdgcn_global_load_lds((const unsigned*)(gb + (size_t)((i) * 64) * ldb + (kt) * 64), (lds_u32*)(sdst + (buf) * STAGE + B_OFF + (i) * 8192), 16, 0, 0)
; DI void gemm3_mainloop(const int wave8, const int lane, const bf16_t* __restrict__ A, int lda, const bf16_t* __restrict__ Bt, int ldb, int K,
;                        unsigned char* smem, f32x4 (&acc)[8][4]) {
;     ...
;     asm volatile("s_waitcnt vmcnt(0)" ::: "memory");
;     G3_LDA(0, 0, 0); G3_LDA(0, 0, 1); G3_LDA(0, 0, 2); G3_LDA(0, 0, 3); G3_LDB(0, 0, 0); G3_LDB(0, 0, 1); G3_LDB(0, 0, 2); G3_LDB(0, 0, 3);
;     asm volatile("s_waitcnt vmcnt(0)" ::: "memory");
;     __builtin_amdgcn_s_barrier();
;     for (int kt = 0; kt < nk; kt += 2) { G3_STEP(0, 1, kt); G3_STEP(1, 0, kt + 1); }
	v_mfma_f32_16x16x32_bf16 v[76:79], v[148:151], v[176:179], v[76:79]
	v_lshl_add_u64 v[196:197], v[130:131], 0, s[2:3]
	v_mfma_f32_16x16x32_bf16 v[72:75], v[152:155], v[176:179], v[72:75]
	v_mfma_f32_16x16x32_bf16 v[68:71], v[156:159], v[176:179], v[68:71]
	v_mfma_f32_16x16x32_bf16 v[64:67], v[160:163], v[176:179], v[64:67]
	global_load_lds_dwordx4 v[164:165], off
	s_waitcnt lgkmcnt(3)
	v_mfma_f32_16x16x32_bf16 v[60:63], v[148:151], v[180:183], v[60:63]
	s_mov_b32 m0, s0
	v_mfma_f32_16x16x32_bf16 v[56:59], v[152:155], v[180:183], v[56:59]
	v_mfma_f32_16x16x32_bf16 v[52:55], v[156:159], v[180:183], v[52:55]
	v_mfma_f32_16x16x32_bf16 v[48:51], v[160:163], v[180:183], v[48:51]
	s_waitcnt lgkmcnt(2)
	v_mfma_f32_16x16x32_bf16 v[44:47], v[148:151], v[184:187], v[44:47]
	v_mfma_f32_16x16x32_bf16 v[40:43], v[152:155], v[184:187], v[40:43]
	v_mfma_f32_16x16x32_bf16 v[36:39], v[156:159], v[184:187], v[36:39]
	v_mfma_f32_16x16x32_bf16 v[28:31], v[160:163], v[184:187], v[28:31]
	s_waitcnt lgkmcnt(1)
	v_mfma_f32_16x16x32_bf16 v[24:27], v[148:151], v[188:191], v[24:27]
	v_mfma_f32_16x16x32_bf16 v[20:23], v[152:155], v[188:191], v[20:23]
	v_mfma_f32_16x16x32_bf16 v[16:19], v[156:159], v[188:191], v[16:19]
	v_mfma_f32_16x16x32_bf16 v[12:15], v[160:163], v[188:191], v[12:15]
	s_waitcnt lgkmcnt(0)
	v_mfma_f32_16x16x32_bf16 v[8:11], v[148:151], v[192:195], v[8:11]
	s_waitcnt vmcnt(0)
	s_barrier
	v_mfma_f32_16x16x32_bf16 v[4:7], v[152:155], v[192:195], v[4:7]
	v_mfma_f32_16x16x32_bf16 v[0:3], v[156:159], v[192:195], v[0:3]
	v_mfma_f32_16x16x32_bf16 v[32:35], v[160:163], v[192:195], v[32:35]
	ds_read_b128 v[148:151], v143
	ds_read_b128 v[164:167], v144
	ds_read_b128 v[152:155], v143 offset:2048
	ds_read_b128 v[156:159], v143 offset:4096
	ds_read_b128 v[160:163], v143 offset:6144
	ds_read_b128 v[168:171], v144 offset:2048
	ds_read_b128 v[172:175], v144 offset:4096
	ds_read_b128 v[176:179], v144 offset:6144
	ds_read_b128 v[180:183], v144 offset:8192
	ds_read_b128 v[184:187], v144 offset:10240
	ds_read_b128 v[188:191], v144 offset:12288
	ds_read_b128 v[192:195], v144 offset:14336
	s_waitcnt lgkmcnt(10)
	v_mfma_f32_16x16x32_bf16 v[124:127], v[148:151], v[164:167], v[124:127]
	s_waitcnt lgkmcnt(9)
	v_mfma_f32_16x16x32_bf16 v[120:123], v[152:155], v[164:167], v[120:123]
	s_waitcnt lgkmcnt(8)
	v_mfma_f32_16x16x32_bf16 v[116:119], v[156:159], v[164:167], v[116:119]
	s_waitcnt lgkmcnt(7)
	v_mfma_f32_16x16x32_bf16 v[112:115], v[160:163], v[164:167], v[112:115]
	global_load_lds_dwordx4 v[196:197], off
	v_lshl_add_u64 v[164:165], v[196:197], 0, s[4:5]
	s_mov_b32 m0, s55
	s_waitcnt lgkmcnt(6)
	v_mfma_f32_16x16x32_bf16 v[108:111], v[148:151], v[168:171], v[108:111]
	v_mfma_f32_16x16x32_bf16 v[104:107], v[152:155], v[168:171], v[104:107]
	v_mfma_f32_16x16x32_bf16 v[100:103], v[156:159], v[168:171], v[100:103]
	v_mfma_f32_16x16x32_bf16 v[96:99], v[160:163], v[168:171], v[96:99]
	global_load_lds_dwordx4 v[164:165], off
	v_lshl_add_u64 v[164:165], v[196:197], 0, s[6:7]
	s_mov_b32 m0, s87
	s_waitcnt lgkmcnt(5)
	v_mfma_f32_16x16x32_bf16 v[92:95], v[148:151], v[172:175], v[92:95]
	v_mfma_f32_16x16x32_bf16 v[88:91], v[152:155], v[172:175], v[88:91]
	v_mfma_f32_16x16x32_bf16 v[84:87], v[156:159], v[172:175], v[84:87]
	v_mfma_f32_16x16x32_bf16 v[80:83], v[160:163], v[172:175], v[80:83]
	global_load_lds_dwordx4 v[164:165], off
	v_lshl_add_u64 v[164:165], v[196:197], 0, s[8:9]
	s_mov_b32 m0, s69
	s_waitcnt lgkmcnt(4)
	v_mfma_f32_16x16x32_bf16 v[76:79], v[148:151], v[176:179], v[76:79]
	v_lshl_add_u64 v[196:197], v[132:133], 0, s[2:3]
	s_mov_b32 s2, s47
	v_mfma_f32_16x16x32_bf16 v[72:75], v[152:155], v[176:179], v[72:75]
	v_mfma_f32_16x16x32_bf16 v[68:71], v[156:159], v[176:179], v[68:71]
	v_mfma_f32_16x16x32_bf16 v[64:67], v[160:163], v[176:179], v[64:67]
	global_load_lds_dwordx4 v[164:165], off
	s_mov_b32 m0, s68
	s_waitcnt lgkmcnt(3)
	v_mfma_f32_16x16x32_bf16 v[60:63], v[148:151], v[180:183], v[60:63]
	v_mfma_f32_16x16x32_bf16 v[56:59], v[152:155], v[180:183], v[56:59]
	v_mfma_f32_16x16x32_bf16 v[52:55], v[156:159], v[180:183], v[52:55]
	v_mfma_f32_16x16x32_bf16 v[48:51], v[160:163], v[180:183], v[48:51]
	s_waitcnt lgkmcnt(2)
	v_mfma_f32_16x16x32_bf16 v[44:47], v[148:151], v[184:187], v[44:47]
	v_mfma_f32_16x16x32_bf16 v[40:43], v[152:155], v[184:187], v[40:43]
	v_mfma_f32_16x16x32_bf16 v[36:39], v[156:159], v[184:187], v[36:39]
	v_mfma_f32_16x16x32_bf16 v[28:31], v[160:163], v[184:187], v[28:31]
	s_waitcnt lgkmcnt(1)
	v_mfma_f32_16x16x32_bf16 v[24:27], v[148:151], v[188:191], v[24:27]
	v_mfma_f32_16x16x32_bf16 v[20:23], v[152:155], v[188:191], v[20:23]
	v_mfma_f32_16x16x32_bf16 v[16:19], v[156:159], v[188:191], v[16:19]
	v_mfma_f32_16x16x32_bf16 v[12:15], v[160:163], v[188:191], v[12:15]
	s_waitcnt lgkmcnt(0)
	v_mfma_f32_16x16x32_bf16 v[8:11], v[148:151], v[192:195], v[8:11]
	v_mfma_f32_16x16x32_bf16 v[4:7], v[152:155], v[192:195], v[4:7]
	v_mfma_f32_16x16x32_bf16 v[0:3], v[156:159], v[192:195], v[0:3]
	v_mfma_f32_16x16x32_bf16 v[32:35], v[160:163], v[192:195], v[32:35]
	ds_read_b128 v[148:151], v145
	ds_read_b128 v[164:167], v146
	ds_read_b128 v[152:155], v145 offset:2048
	ds_read_b128 v[156:159], v145 offset:4096
	ds_read_b128 v[160:163], v145 offset:6144
	ds_read_b128 v[168:171], v146 offset:2048
	ds_read_b128 v[172:175], v146 offset:4096
	ds_read_b128 v[176:179], v146 offset:6144
	ds_read_b128 v[180:183], v146 offset:8192
	ds_read_b128 v[184:187], v146 offset:10240
	ds_read_b128 v[188:191], v146 offset:12288
	ds_read_b128 v[192:195], v146 offset:14336
	s_waitcnt lgkmcnt(10)
	v_mfma_f32_16x16x32_bf16 v[124:127], v[148:151], v[164:167], v[124:127]
	s_waitcnt lgkmcnt(9)
; #define G3_LDA(buf, kt, i) __builtin_amdgcn_global_load_lds((const unsigned*)(ga + (size_t)((i) * 64) * lda + (kt) * 64), (lds_u32*)(sdst + (buf) * STAGE + (i) * 8192), 16, 0, 0)
; #define G3_LDB(buf, kt, i) __builtin_amdgcn_global_load_lds((const unsigned*)(gb + (size_t)((i) * 64) * ldb + (kt) * 64), (lds_u32*)(sdst + (buf) * STAGE + B_OFF + (i) * 8192), 16, 0, 0)
; DI void gemm3_mainloop(const int wave8, const int lane, const bf16_t* __restrict__ A, int lda, const bf16_t* __restrict__ Bt, int ldb, int K,
;                        unsigned char* smem, f32x4 (&acc)[8][4]) {
;     ...
;     asm volatile("s_waitcnt vmcnt(0)" ::: "memory");
;     G3_LDA(0, 0, 0); G3_LDA(0, 0, 1); G3_LDA(0, 0, 2); G3_LDA(0, 0, 3); G3_LDB(0, 0, 0); G3_LDB(0, 0, 1); G3_LDB(0, 0, 2); G3_LDB(0, 0, 3);
;     asm volatile("s_waitcnt vmcnt(0)" ::: "memory");
;     __builtin_amdgcn_s_barrier();
;     for (int kt = 0; kt < nk; kt += 2) { G3_STEP(0, 1, kt); G3_STEP(1, 0, kt + 1); }
; DI void phase4(const Params& p, unsigned char* smem) {
;     ...
; #pragma unroll
;         for (int i = 0; i < 8; ++i) {
;             const size_t m = (size_t)mt * 256 + wm * 128 + i * 16 + fr;
; #pragma unroll
;             for (int j = 0; j < 4; ++j) {
;                 const int c = nt * 256 + wn * 64 + j * 16 + fq * 4;
;                 const f32x4 xv = *(const f32x4*)(p.x + m * DM + c);
;                 *(f32x4*)(p.out + m * DM + c) = xv + acc[i][j];
;             }
;         }
	v_mfma_f32_16x16x32_bf16 v[120:123], v[152:155], v[164:167], v[120:123]
	s_waitcnt lgkmcnt(8)
	v_mfma_f32_16x16x32_bf16 v[116:119], v[156:159], v[164:167], v[116:119]
	s_waitcnt lgkmcnt(7)
	v_mfma_f32_16x16x32_bf16 v[112:115], v[160:163], v[164:167], v[112:115]
	global_load_lds_dwordx4 v[196:197], off
	v_lshl_add_u64 v[164:165], v[196:197], 0, s[4:5]
	s_mov_b32 m0, s39
	s_waitcnt lgkmcnt(6)
	v_mfma_f32_16x16x32_bf16 v[108:111], v[148:151], v[168:171], v[108:111]
	v_mfma_f32_16x16x32_bf16 v[104:107], v[152:155], v[168:171], v[104:107]
	v_mfma_f32_16x16x32_bf16 v[100:103], v[156:159], v[168:171], v[100:103]
	v_mfma_f32_16x16x32_bf16 v[96:99], v[160:163], v[168:171], v[96:99]
	global_load_lds_dwordx4 v[164:165], off
	v_lshl_add_u64 v[164:165], v[196:197], 0, s[6:7]
	s_mov_b32 m0, s38
	s_waitcnt lgkmcnt(5)
	v_mfma_f32_16x16x32_bf16 v[92:95], v[148:151], v[172:175], v[92:95]
	v_mfma_f32_16x16x32_bf16 v[88:91], v[152:155], v[172:175], v[88:91]
	v_mfma_f32_16x16x32_bf16 v[84:87], v[156:159], v[172:175], v[84:87]
	v_mfma_f32_16x16x32_bf16 v[80:83], v[160:163], v[172:175], v[80:83]
	global_load_lds_dwordx4 v[164:165], off
	v_lshl_add_u64 v[164:165], v[196:197], 0, s[8:9]
	s_mov_b32 m0, s1
	s_waitcnt lgkmcnt(4)
	v_mfma_f32_16x16x32_bf16 v[76:79], v[148:151], v[176:179], v[76:79]
	v_mfma_f32_16x16x32_bf16 v[72:75], v[152:155], v[176:179], v[72:75]
	v_mfma_f32_16x16x32_bf16 v[68:71], v[156:159], v[176:179], v[68:71]
	v_mfma_f32_16x16x32_bf16 v[64:67], v[160:163], v[176:179], v[64:67]
	global_load_lds_dwordx4 v[164:165], off
	s_waitcnt lgkmcnt(3)
	v_mfma_f32_16x16x32_bf16 v[60:63], v[148:151], v[180:183], v[60:63]
	v_mfma_f32_16x16x32_bf16 v[56:59], v[152:155], v[180:183], v[56:59]
	v_mfma_f32_16x16x32_bf16 v[52:55], v[156:159], v[180:183], v[52:55]
	v_mfma_f32_16x16x32_bf16 v[48:51], v[160:163], v[180:183], v[48:51]
	s_waitcnt lgkmcnt(2)
	v_mfma_f32_16x16x32_bf16 v[44:47], v[148:151], v[184:187], v[44:47]
	v_mfma_f32_16x16x32_bf16 v[40:43], v[152:155], v[184:187], v[40:43]
	v_mfma_f32_16x16x32_bf16 v[36:39], v[156:159], v[184:187], v[36:39]
	v_mfma_f32_16x16x32_bf16 v[28:31], v[160:163], v[184:187], v[28:31]
	s_waitcnt lgkmcnt(1)
	v_mfma_f32_16x16x32_bf16 v[24:27], v[148:151], v[188:191], v[24:27]
	v_mfma_f32_16x16x32_bf16 v[20:23], v[152:155], v[188:191], v[20:23]
	v_mfma_f32_16x16x32_bf16 v[16:19], v[156:159], v[188:191], v[16:19]
	v_mfma_f32_16x16x32_bf16 v[12:15], v[160:163], v[188:191], v[12:15]
	s_waitcnt lgkmcnt(0)
	v_mfma_f32_16x16x32_bf16 v[8:11], v[148:151], v[192:195], v[8:11]
	s_waitcnt vmcnt(0)
	s_barrier
	v_mfma_f32_16x16x32_bf16 v[4:7], v[152:155], v[192:195], v[4:7]
	v_mfma_f32_16x16x32_bf16 v[0:3], v[156:159], v[192:195], v[0:3]
	v_mfma_f32_16x16x32_bf16 v[32:35], v[160:163], v[192:195], v[32:35]
	s_cbranch_vccnz .LBB0_503
	v_lshrrev_b32_e32 v130, 2, v138
	s_lshl_b32 s2, s46, 8
	v_and_b32_e32 v130, 12, v130
	s_add_i32 s2, s2, s54
	v_lshl_or_b32 v130, s45, 8, v130
	v_and_or_b32 v128, v138, 15, s2
	v_or_b32_e32 v132, s82, v130
	v_lshlrev_b64 v[130:131], 13, v[128:129]
	v_ashrrev_i32_e32 v133, 31, v132
	v_lshl_add_u64 v[134:135], s[40:41], 0, v[130:131]
	v_lshlrev_b64 v[132:133], 2, v[132:133]
	v_lshl_add_u64 v[138:139], v[134:135], 0, v[132:133]
	global_load_dwordx4 v[134:137], v[138:139], off
	v_lshl_add_u64 v[140:141], s[70:71], 0, v[130:131]
	v_lshl_add_u64 v[140:141], v[140:141], 0, v[132:133]
	s_lshr_b32 s2, s33, 3
	s_add_i32 s44, s44, s84
	s_add_i32 s37, s37, s2
	s_cmp_gt_i32 s44, 31
	s_waitcnt vmcnt(0)
	v_pk_add_f32 v[126:127], v[126:127], v[136:137]
	v_pk_add_f32 v[124:125], v[124:125], v[134:135]
	global_store_dwordx4 v[140:141], v[124:127], off
	global_load_dwordx4 v[124:127], v[138:139], off offset:64
	s_waitcnt vmcnt(0)
	v_pk_add_f32 v[122:123], v[122:123], v[126:127]
	v_pk_add_f32 v[120:121], v[120:121], v[124:125]
	global_store_dwordx4 v[140:141], v[120:123], off offset:64
	global_load_dwordx4 v[120:123], v[138:139], off offset:128
	s_waitcnt vmcnt(0)
	v_pk_add_f32 v[118:119], v[118:119], v[122:123]
	v_pk_add_f32 v[116:117], v[116:117], v[120:121]
	global_store_dwordx4 v[140:141], v[116:119], off offset:128
	global_load_dwordx4 v[116:119], v[138:139], off offset:192
	v_or_b32_e32 v120, 0x20000, v130
	v_mov_b32_e32 v121, v131
	v_lshl_add_u64 v[122:123], s[40:41], 0, v[120:121]
	v_lshl_add_u64 v[122:123], v[122:123], 0, v[132:133]
	s_waitcnt vmcnt(0)
	v_pk_add_f32 v[114:115], v[114:115], v[118:119]
	v_pk_add_f32 v[112:113], v[112:113], v[116:117]
	global_store_dwordx4 v[140:141], v[112:115], off offset:192
	global_load_dwordx4 v[112:115], v[122:123], off
	v_lshl_add_u64 v[116:117], s[70:71], 0, v[120:121]
	v_lshl_add_u64 v[116:117], v[116:117], 0, v[132:133]
	s_waitcnt vmcnt(0)
	v_pk_add_f32 v[110:111], v[110:111], v[114:115]
	v_pk_add_f32 v[108:109], v[108:109], v[112:113]
	global_store_dwordx4 v[116:117], v[108:111], off
	global_load_dwordx4 v[108:111], v[122:123], off offset:64
	s_waitcnt vmcnt(0)
	v_pk_add_f32 v[106:107], v[106:107], v[110:111]
	v_pk_add_f32 v[104:105], v[104:105], v[108:109]
	global_store_dwordx4 v[116:117], v[104:107], off offset:64
	global_load_dwordx4 v[104:107], v[122:123], off offset:128
	s_waitcnt vmcnt(0)
	v_pk_add_f32 v[102:103], v[102:103], v[106:107]
	v_pk_add_f32 v[100:101], v[100:101], v[104:105]
	global_store_dwordx4 v[116:117], v[100:103], off offset:128
	global_load_dwordx4 v[100:103], v[122:123], off offset:192
	v_or_b32_e32 v104, 0x40000, v130
	v_mov_b32_e32 v105, v131
	v_lshl_add_u64 v[106:107], s[40:41], 0, v[104:105]
	v_lshl_add_u64 v[106:107], v[106:107], 0, v[132:133]
	s_waitcnt vmcnt(0)
; template <typename F> DI void for_tiles3(int MT, int NT, F f) {
;     const int b = blockIdx.x, G = gridDim.x, xcd = b & 7, slot = b >> 3, slots = G >> 3;
;     const int nsn = NT / 4, nsm = MT / 8;
;     for (int sidx = xcd; sidx < nsn * nsm; sidx += 8) {
;         const int sm = sidx / nsn, sn = sidx % nsn;
;         for (int tl = slot; tl < 32; tl += slots) f(sm * 8 + (tl & 7), sn * 4 + (tl >> 3));
;     }
; DI void phase4(const Params& p, unsigned char* smem) {
;     ...
; #pragma unroll
;         for (int i = 0; i < 8; ++i) {
;             const size_t m = (size_t)mt * 256 + wm * 128 + i * 16 + fr;
; #pragma unroll
;             for (int j = 0; j < 4; ++j) {
;                 const int c = nt * 256 + wn * 64 + j * 16 + fq * 4;
;                 const f32x4 xv = *(const f32x4*)(p.x + m * DM + c);
;                 *(f32x4*)(p.out + m * DM + c) = xv + acc[i][j];
;             }
;         }
	v_pk_add_f32 v[98:99], v[98:99], v[102:103]
	v_pk_add_f32 v[96:97], v[96:97], v[100:101]
	global_store_dwordx4 v[116:117], v[96:99], off offset:192
	global_load_dwordx4 v[96:99], v[106:107], off
	v_lshl_add_u64 v[100:101], s[70:71], 0, v[104:105]
	v_lshl_add_u64 v[100:101], v[100:101], 0, v[132:133]
	s_waitcnt vmcnt(0)
	v_pk_add_f32 v[94:95], v[94:95], v[98:99]
	v_pk_add_f32 v[92:93], v[92:93], v[96:97]
	global_store_dwordx4 v[100:101], v[92:95], off
	global_load_dwordx4 v[92:95], v[106:107], off offset:64
	s_waitcnt vmcnt(0)
	v_pk_add_f32 v[90:91], v[90:91], v[94:95]
	v_pk_add_f32 v[88:89], v[88:89], v[92:93]
	global_store_dwordx4 v[100:101], v[88:91], off offset:64
	global_load_dwordx4 v[88:91], v[106:107], off offset:128
	s_waitcnt vmcnt(0)
	v_pk_add_f32 v[86:87], v[86:87], v[90:91]
	v_pk_add_f32 v[84:85], v[84:85], v[88:89]
	global_store_dwordx4 v[100:101], v[84:87], off offset:128
	global_load_dwordx4 v[84:87], v[106:107], off offset:192
	v_or_b32_e32 v88, 0x60000, v130
	v_mov_b32_e32 v89, v131
	v_lshl_add_u64 v[90:91], s[40:41], 0, v[88:89]
	v_lshl_add_u64 v[90:91], v[90:91], 0, v[132:133]
	s_waitcnt vmcnt(0)
	v_pk_add_f32 v[82:83], v[82:83], v[86:87]
	v_pk_add_f32 v[80:81], v[80:81], v[84:85]
	global_store_dwordx4 v[100:101], v[80:83], off offset:192
	global_load_dwordx4 v[80:83], v[90:91], off
	v_lshl_add_u64 v[84:85], s[70:71], 0, v[88:89]
	v_lshl_add_u64 v[84:85], v[84:85], 0, v[132:133]
	s_waitcnt vmcnt(0)
	v_pk_add_f32 v[78:79], v[78:79], v[82:83]
	v_pk_add_f32 v[76:77], v[76:77], v[80:81]
	global_store_dwordx4 v[84:85], v[76:79], off
	global_load_dwordx4 v[76:79], v[90:91], off offset:64
	s_waitcnt vmcnt(0)
	v_pk_add_f32 v[74:75], v[74:75], v[78:79]
	v_pk_add_f32 v[72:73], v[72:73], v[76:77]
	global_store_dwordx4 v[84:85], v[72:75], off offset:64
	global_load_dwordx4 v[72:75], v[90:91], off offset:128
	s_waitcnt vmcnt(0)
	v_pk_add_f32 v[70:71], v[70:71], v[74:75]
	v_pk_add_f32 v[68:69], v[68:69], v[72:73]
	global_store_dwordx4 v[84:85], v[68:71], off offset:128
	global_load_dwordx4 v[68:71], v[90:91], off offset:192
	v_or_b32_e32 v72, 0x80000, v130
	v_mov_b32_e32 v73, v131
	v_lshl_add_u64 v[74:75], s[40:41], 0, v[72:73]
	v_lshl_add_u64 v[74:75], v[74:75], 0, v[132:133]
	s_waitcnt vmcnt(0)
	v_pk_add_f32 v[66:67], v[66:67], v[70:71]
	v_pk_add_f32 v[64:65], v[64:65], v[68:69]
	global_store_dwordx4 v[84:85], v[64:67], off offset:192
	global_load_dwordx4 v[64:67], v[74:75], off
	v_lshl_add_u64 v[68:69], s[70:71], 0, v[72:73]
	v_lshl_add_u64 v[68:69], v[68:69], 0, v[132:133]
	s_waitcnt vmcnt(0)
	v_pk_add_f32 v[62:63], v[62:63], v[66:67]
	v_pk_add_f32 v[60:61], v[60:61], v[64:65]
	global_store_dwordx4 v[68:69], v[60:63], off
	global_load_dwordx4 v[60:63], v[74:75], off offset:64
	s_waitcnt vmcnt(0)
	v_pk_add_f32 v[58:59], v[58:59], v[62:63]
	v_pk_add_f32 v[56:57], v[56:57], v[60:61]
	global_store_dwordx4 v[68:69], v[56:59], off offset:64
	global_load_dwordx4 v[56:59], v[74:75], off offset:128
	s_waitcnt vmcnt(0)
	v_pk_add_f32 v[54:55], v[54:55], v[58:59]
	v_pk_add_f32 v[52:53], v[52:53], v[56:57]
	global_store_dwordx4 v[68:69], v[52:55], off offset:128
	global_load_dwordx4 v[52:55], v[74:75], off offset:192
	v_or_b32_e32 v56, 0xa0000, v130
	v_mov_b32_e32 v57, v131
	v_lshl_add_u64 v[58:59], s[40:41], 0, v[56:57]
	v_lshl_add_u64 v[58:59], v[58:59], 0, v[132:133]
	s_waitcnt vmcnt(0)
	v_pk_add_f32 v[50:51], v[50:51], v[54:55]
	v_pk_add_f32 v[48:49], v[48:49], v[52:53]
	global_store_dwordx4 v[68:69], v[48:51], off offset:192
	global_load_dwordx4 v[48:51], v[58:59], off
	v_lshl_add_u64 v[52:53], s[70:71], 0, v[56:57]
	v_lshl_add_u64 v[52:53], v[52:53], 0, v[132:133]
	s_waitcnt vmcnt(0)
	v_pk_add_f32 v[46:47], v[46:47], v[50:51]
	v_pk_add_f32 v[44:45], v[44:45], v[48:49]
	global_store_dwordx4 v[52:53], v[44:47], off
	global_load_dwordx4 v[44:47], v[58:59], off offset:64
	s_waitcnt vmcnt(0)
	v_pk_add_f32 v[42:43], v[42:43], v[46:47]
	v_pk_add_f32 v[40:41], v[40:41], v[44:45]
	global_store_dwordx4 v[52:53], v[40:43], off offset:64
	global_load_dwordx4 v[40:43], v[58:59], off offset:128
	s_waitcnt vmcnt(0)
	v_pk_add_f32 v[38:39], v[38:39], v[42:43]
	v_pk_add_f32 v[36:37], v[36:37], v[40:41]
	global_store_dwordx4 v[52:53], v[36:39], off offset:128
	global_load_dwordx4 v[36:39], v[58:59], off offset:192
	v_or_b32_e32 v40, 0xc0000, v130
	v_mov_b32_e32 v41, v131
	v_lshl_add_u64 v[42:43], s[40:41], 0, v[40:41]
	v_lshl_add_u64 v[42:43], v[42:43], 0, v[132:133]
	v_or_b32_e32 v130, 0xe0000, v130
	s_waitcnt vmcnt(0)
	v_pk_add_f32 v[30:31], v[30:31], v[38:39]
	v_pk_add_f32 v[28:29], v[28:29], v[36:37]
	global_store_dwordx4 v[52:53], v[28:31], off offset:192
	global_load_dwordx4 v[28:31], v[42:43], off
	v_lshl_add_u64 v[36:37], s[70:71], 0, v[40:41]
	v_lshl_add_u64 v[36:37], v[36:37], 0, v[132:133]
	s_waitcnt vmcnt(0)
	v_pk_add_f32 v[26:27], v[26:27], v[30:31]
	v_pk_add_f32 v[24:25], v[24:25], v[28:29]
	global_store_dwordx4 v[36:37], v[24:27], off
	global_load_dwordx4 v[24:27], v[42:43], off offset:64
	s_waitcnt vmcnt(0)
	v_pk_add_f32 v[22:23], v[22:23], v[26:27]
	v_pk_add_f32 v[20:21], v[20:21], v[24:25]
	global_store_dwordx4 v[36:37], v[20:23], off offset:64
	global_load_dwordx4 v[20:23], v[42:43], off offset:128
	s_waitcnt vmcnt(0)
	v_pk_add_f32 v[18:19], v[18:19], v[22:23]
	v_pk_add_f32 v[16:17], v[16:17], v[20:21]
	global_store_dwordx4 v[36:37], v[16:19], off offset:128
	global_load_dwordx4 v[16:19], v[42:43], off offset:192
	v_lshl_add_u64 v[20:21], s[40:41], 0, v[130:131]
	v_lshl_add_u64 v[20:21], v[20:21], 0, v[132:133]
	s_waitcnt vmcnt(0)
	v_pk_add_f32 v[14:15], v[14:15], v[18:19]
	v_pk_add_f32 v[12:13], v[12:13], v[16:17]
	global_store_dwordx4 v[36:37], v[12:15], off offset:192
	global_load_dwordx4 v[12:15], v[20:21], off
	v_lshl_add_u64 v[16:17], s[70:71], 0, v[130:131]
	v_lshl_add_u64 v[16:17], v[16:17], 0, v[132:133]
	s_waitcnt vmcnt(0)
	v_pk_add_f32 v[10:11], v[10:11], v[14:15]
	v_pk_add_f32 v[8:9], v[8:9], v[12:13]
	global_store_dwordx4 v[16:17], v[8:11], off
	global_load_dwordx4 v[8:11], v[20:21], off offset:64
	s_waitcnt vmcnt(0)
	v_pk_add_f32 v[6:7], v[6:7], v[10:11]
	v_pk_add_f32 v[4:5], v[4:5], v[8:9]
	global_store_dwordx4 v[16:17], v[4:7], off offset:64
	global_load_dwordx4 v[4:7], v[20:21], off offset:128
	s_waitcnt vmcnt(0)
	v_pk_add_f32 v[2:3], v[2:3], v[6:7]
	v_pk_add_f32 v[0:1], v[0:1], v[4:5]
	global_store_dwordx4 v[16:17], v[0:3], off offset:128
	global_load_dwordx4 v[0:3], v[20:21], off offset:192
	s_waitcnt vmcnt(0)
	v_pk_add_f32 v[2:3], v[34:35], v[2:3]
	v_pk_add_f32 v[0:1], v[32:33], v[0:1]
	global_store_dwordx4 v[16:17], v[0:3], off offset:192
	s_cbranch_scc0 .LBB0_502
	s_branch .LBB0_499
